# grid barrier entry: the two set-up words are read from LDS back to back (one LDS latency instead of two); plus K-loop second k-step literal offsets
# baseline (speedup 1.0000x reference)
; __device__ __forceinline__ void xcd_barrier(const XcdBarrier& b) {
;     asm volatile("s_waitcnt vmcnt(0)" ::: "memory");
;     __syncthreads();
;     if (threadIdx.x == 0) {
;         unsigned* bar = b.bar;
;         __builtin_amdgcn_s_waitcnt(0);
;         unsigned nloc = b.st[0], nx = b.st[1];
;         if (nloc == 0u) { xcd_barrier_complete(bar, b.x, nloc, nx); b.st[0] = nloc; b.st[1] = nx; }
.LBB0_21:
	s_cmp_le_i32 s47, s48
	s_cbranch_scc1 .LBB0_75
	s_waitcnt vmcnt(0)
	s_barrier
	s_mov_b64 s[0:1], exec
	v_readlane_b32 s10, v251, 4
	v_readlane_b32 s11, v251, 5
	s_and_b64 s[10:11], s[0:1], s[10:11]
	s_mov_b64 exec, s[10:11]
	s_cbranch_execz .Lxb_other
	v_readlane_b32 s3, v249, 32
	v_readlane_b32 s14, v249, 33
	s_waitcnt vmcnt(0) expcnt(0) lgkmcnt(0)
	s_nop 0
	v_mov_b32_e32 v0, s3
	v_mov_b32_e32 v2, s14
	ds_read_b32 v3, v0
	ds_read_b32 v0, v2
	s_waitcnt lgkmcnt(1)
	v_cmp_ne_u32_e32 vcc, 0, v3
	s_cbranch_vccnz .LBB0_38
	s_mov_b32 s3, 1
	s_branch .LBB0_26
